# scan wave-7 p conversion: loads issued two steps ahead (double-buffered) with a counted vmcnt(4) instead of vmcnt(0) every step
# baseline (speedup 1.0000x reference)
.LBB0_384:
	s_or_b64 exec, exec, s[68:69]
	s_lshr_b32 s75, s74, 6
	s_cmpk_gt_u32 s74, 0xff
	s_mov_b64 s[0:1], -1
	s_cbranch_scc0 .LBB0_396
	s_setprio 1
	s_and_b32 s0, s94, 15
	s_lshl_b32 s72, s0, 22
	s_add_i32 s73, s75, -4
	s_cmp_lg_u32 s73, 0
	s_cselect_b64 s[0:1], -1, 0
	s_cmpk_lt_u32 s74, 0x1c0
	s_cselect_b64 s[68:69], -1, 0
	s_not_b32 s70, s75
	s_lshl_b32 s70, s70, 5
	s_and_b32 s87, s70, 32
	s_add_i32 s70, s75, -5
	v_or_b32_e32 v2, s87, v83
	s_cmp_lt_u32 s70, 2
	v_mul_u32_u24_e32 v3, 0x110, v2
	s_cselect_b64 s[70:71], -1, 0
	v_mul_u32_u24_e32 v105, 0x50, v2
	v_lshl_add_u32 v106, s73, 7, v90
	v_lshl_or_b32 v2, s73, 5, v83
	v_lshl_add_u32 v108, s73, 6, v91
	s_add_i32 s73, s87, s95
	s_waitcnt lgkmcnt(0)
	s_barrier
	s_add_i32 s73, s73, s86
	s_waitcnt lgkmcnt(0)
	s_barrier
	s_movk_i32 s88, 0x50
	s_lshl_b32 s73, s73, 1
	v_mul_lo_u32 v107, v2, s88
	s_or_b32 s72, s72, s73
	s_mov_b32 s73, s96
	v_mov_b32_e32 v2, 0
	s_mov_b32 s87, 1
	v_lshl_add_u64 v[80:81], v[78:79], 0, s[72:73]
	v_add_u32_e32 v109, v86, v3
	v_mov_b32_e32 v3, v2
	v_mov_b32_e32 v4, v2
	v_mov_b32_e32 v5, v2
	s_waitcnt vmcnt(0)
	v_mov_b32_e32 v6, v2
	v_mov_b32_e32 v7, v2
	v_mov_b32_e32 v8, v2
	v_mov_b32_e32 v9, v2
	v_mov_b32_e32 v10, v2
	v_mov_b32_e32 v11, v2
	v_mov_b32_e32 v12, v2
	v_mov_b32_e32 v13, v2
	v_mov_b32_e32 v14, v2
	v_mov_b32_e32 v15, v2
	v_mov_b32_e32 v16, v2
	v_mov_b32_e32 v17, v2
	v_mov_b32_e32 v18, v2
	v_mov_b32_e32 v19, v2
	v_mov_b32_e32 v20, v2
	v_mov_b32_e32 v21, v2
	v_mov_b32_e32 v22, v2
	v_mov_b32_e32 v23, v2
	v_mov_b32_e32 v24, v2
	v_mov_b32_e32 v25, v2
	v_mov_b32_e32 v26, v2
	v_mov_b32_e32 v27, v2
	v_mov_b32_e32 v28, v2
	v_mov_b32_e32 v29, v2
	v_mov_b32_e32 v30, v2
	v_mov_b32_e32 v31, v2
	v_mov_b32_e32 v32, v2
	v_mov_b32_e32 v33, v2
	s_and_b64 vcc, exec, s[68:69]
	s_cbranch_vccnz .Lmy_pc0_nosetup
	v_readlane_b32 s98, v255, 3
	v_readlane_b32 s99, v255, 4
	v_readlane_b32 s100, v255, 17
	s_nop 3
	s_lshl_b32 s101, s100, 18
	s_add_u32 s98, s98, s101
	s_addc_u32 s99, s99, 0
	v_lshlrev_b32_e32 v232, 4, v158
	v_mov_b32_e32 v233, 0
	v_lshl_add_u64 v[232:233], s[98:99], 0, v[232:233]
	s_lshl_b32 s101, s100, 17
	s_add_u32 s98, s80, s101
	s_addc_u32 s99, s81, 0
	s_add_u32 s98, s98, 0x34000000
	s_addc_u32 s99, s99, 0
	v_lshlrev_b32_e32 v234, 3, v158
	v_mov_b32_e32 v235, 0
	v_lshl_add_u64 v[234:235], s[98:99], 0, v[234:235]
	v_mov_b32_e32 v236, 0x800
	v_mov_b32_e32 v237, 0
	v_mov_b32_e32 v238, 0x400
	v_mov_b32_e32 v239, 0
	v_mov_b32_e32 v244, 0x100
	v_mov_b32_e32 v245, 0
	v_mov_b32_e32 v202, 0x1000
	v_mov_b32_e32 v203, 0
	v_mov_b32_e32 v195, 0
	global_load_dwordx4 v[224:227], v[232:233], off
	global_load_dwordx4 v[228:231], v[232:233], off offset:1024
	v_lshl_add_u64 v[232:233], v[232:233], 0, v[236:237]
	global_load_dwordx4 v[246:249], v[232:233], off
	global_load_dwordx4 v[250:253], v[232:233], off offset:1024
	v_lshl_add_u64 v[232:233], v[232:233], 0, v[236:237]

.Lmy_pc0:
	s_add_i32 s32, s87, -1
	s_cmp_lt_u32 s32, 20
	s_cbranch_scc1 .Lmy_tw0_w0
	s_cmp_gt_u32 s32, 126
	s_cbranch_scc1 .Lmy_tw0_w0
	s_waitcnt vmcnt(4)
	s_branch .Lmy_tw0_wd

.Lmy_tw0_wd:
	s_bitcmp1_b32 s32, 0
	s_cbranch_scc1 .Lmy_tw0_odd
	v_cvt_pk_bf16_f32 v240, v224, v225
	v_cvt_pk_bf16_f32 v241, v226, v227
	v_cvt_pk_bf16_f32 v242, v228, v229
	v_cvt_pk_bf16_f32 v243, v230, v231
	s_branch .Lmy_tw0_cvd
.Lmy_tw0_odd:
	v_cvt_pk_bf16_f32 v240, v246, v247
	v_cvt_pk_bf16_f32 v241, v248, v249
	v_cvt_pk_bf16_f32 v242, v250, v251
	v_cvt_pk_bf16_f32 v243, v252, v253
.Lmy_tw0_cvd:
	global_store_dwordx2 v[234:235], v[240:241], off
	global_store_dwordx2 v[234:235], v[242:243], off offset:512
	v_lshl_add_u64 v[234:235], v[234:235], 0, v[238:239]
	s_cmp_gt_u32 s32, 18
	s_cbranch_scc1 .Lmy_tw0_done
	s_cmp_eq_u32 s32, 0
	s_cbranch_scc0 .Lmy_tw0_fin
	v_readlane_b32 s100, v255, 17
	v_readlane_b32 s98, v255, 41
	v_readlane_b32 s99, v255, 42
	s_nop 3
	s_lshr_b32 s101, s100, 1
	s_lshl_b32 s101, s101, 15
	s_add_u32 s98, s98, s101
	s_addc_u32 s99, s99, 0
	s_and_b32 s101, s100, 1
	s_lshl_b32 s101, s101, 11
	s_add_u32 s98, s98, s101
	s_addc_u32 s99, s99, 0
	v_lshlrev_b32_e32 v200, 2, v158
	v_mov_b32_e32 v201, 0
	v_lshl_add_u64 v[160:161], s[98:99], 0, v[200:201]
	v_lshl_add_u64 v[162:163], v[160:161], 0, v[202:203]
	v_lshl_add_u64 v[164:165], v[162:163], 0, v[202:203]
	v_lshl_add_u64 v[166:167], v[164:165], 0, v[202:203]
	v_lshl_add_u64 v[168:169], v[166:167], 0, v[202:203]
	v_lshl_add_u64 v[170:171], v[168:169], 0, v[202:203]
	v_lshl_add_u64 v[172:173], v[170:171], 0, v[202:203]
	v_lshl_add_u64 v[174:175], v[172:173], 0, v[202:203]
	s_add_u32 s98, s80, 0x36900000
	s_addc_u32 s99, s81, 0
	s_and_b32 s101, s100, 1
	s_lshl_b32 s101, s101, 20
	s_add_u32 s98, s98, s101
	s_addc_u32 s99, s99, 0
	s_lshr_b32 s101, s100, 1
	s_lshl_b32 s101, s101, 4
	s_add_u32 s98, s98, s101
	s_addc_u32 s99, s99, 0
	v_lshlrev_b32_e32 v200, 11, v158
	v_mov_b32_e32 v194, 0x20000
	v_lshl_add_u64 v[192:193], s[98:99], 0, v[200:201]
	s_branch .Lmy_tw0_issue

.Lmy_tw0_done:
	s_cmp_gt_u32 s32, 125
	s_cbranch_scc1 .LBB0_392
	s_bitcmp1_b32 s32, 0
	s_cbranch_scc1 .Lmy_tw0_ldodd
	global_load_dwordx4 v[224:227], v[232:233], off
	global_load_dwordx4 v[228:231], v[232:233], off offset:1024
	v_lshl_add_u64 v[232:233], v[232:233], 0, v[236:237]
	s_branch .LBB0_392
.Lmy_tw0_ldodd:
	global_load_dwordx4 v[246:249], v[232:233], off
	global_load_dwordx4 v[250:253], v[232:233], off offset:1024
	v_lshl_add_u64 v[232:233], v[232:233], 0, v[236:237]
	s_branch .LBB0_392

.LBB0_415:
	s_or_b64 exec, exec, s[68:69]
	v_readfirstlane_b32 s88, v0
	s_lshl_b32 s0, s94, 12
	s_lshr_b32 s87, s88, 6
	s_cmpk_gt_u32 s88, 0xff
	s_mov_b64 s[68:69], -1
	s_cbranch_scc0 .LBB0_427
	s_setprio 1
	s_mov_b32 s1, s96
	s_lshl_b64 s[74:75], s[0:1], 10
	s_add_i32 s92, s87, -4
	s_cmp_lg_u32 s92, 0
	s_cselect_b64 s[68:69], -1, 0
	s_cmpk_lt_u32 s88, 0x1c0
	s_cselect_b64 s[70:71], -1, 0
	s_not_b32 s72, s87
	s_lshl_b32 s72, s72, 5
	s_and_b32 s93, s72, 32
	s_add_i32 s72, s87, -5
	v_or_b32_e32 v2, s93, v83
	s_cmp_lt_u32 s72, 2
	v_mul_u32_u24_e32 v3, 0x110, v2
	s_cselect_b64 s[72:73], -1, 0
	v_mul_u32_u24_e32 v105, 0x50, v2
	v_lshl_add_u32 v106, s92, 7, v90
	v_lshl_or_b32 v2, s92, 5, v83
	v_lshl_add_u32 v108, s92, 6, v91
	s_add_i32 s92, s93, s95
	s_add_i32 s92, s92, s86
	s_waitcnt lgkmcnt(0)
	s_barrier
	s_lshl_b32 s86, s92, 1
	s_waitcnt lgkmcnt(0)
	s_barrier
	s_movk_i32 vcc_lo, 0x50
	s_add_u32 s74, s74, s86
	v_mul_lo_u32 v107, v2, vcc_lo
	s_addc_u32 s75, s75, 0
	v_mov_b32_e32 v2, 0
	s_mov_b32 s1, 0
	v_lshl_add_u64 v[80:81], v[76:77], 0, s[74:75]
	s_mov_b64 s[74:75], 0
	v_add_u32_e32 v109, v86, v3
	v_mov_b32_e32 v3, v2
	v_mov_b32_e32 v4, v2
	v_mov_b32_e32 v5, v2
	s_waitcnt vmcnt(0)
	v_mov_b32_e32 v6, v2
	v_mov_b32_e32 v7, v2
	v_mov_b32_e32 v8, v2
	v_mov_b32_e32 v9, v2
	v_mov_b32_e32 v10, v2
	v_mov_b32_e32 v11, v2
	v_mov_b32_e32 v12, v2
	v_mov_b32_e32 v13, v2
	v_mov_b32_e32 v14, v2
	v_mov_b32_e32 v15, v2
	v_mov_b32_e32 v16, v2
	v_mov_b32_e32 v17, v2
	v_mov_b32_e32 v18, v2
	v_mov_b32_e32 v19, v2
	v_mov_b32_e32 v20, v2
	v_mov_b32_e32 v21, v2
	v_mov_b32_e32 v22, v2
	v_mov_b32_e32 v23, v2
	v_mov_b32_e32 v24, v2
	v_mov_b32_e32 v25, v2
	v_mov_b32_e32 v26, v2
	v_mov_b32_e32 v27, v2
	v_mov_b32_e32 v28, v2
	v_mov_b32_e32 v29, v2
	v_mov_b32_e32 v30, v2
	v_mov_b32_e32 v31, v2
	v_mov_b32_e32 v32, v2
	v_mov_b32_e32 v33, v2
	s_and_b64 vcc, exec, s[70:71]
	s_cbranch_vccnz .Lmy_pc1_nosetup
	v_readlane_b32 s98, v255, 3
	v_readlane_b32 s99, v255, 4
	v_readlane_b32 s100, v255, 17
	s_nop 3
	s_lshl_b32 s101, s100, 18
	s_add_u32 s98, s98, s101
	s_addc_u32 s99, s99, 0
	v_lshlrev_b32_e32 v232, 4, v158
	v_mov_b32_e32 v233, 0
	v_lshl_add_u64 v[232:233], s[98:99], 0, v[232:233]
	s_lshl_b32 s101, s100, 17
	s_add_u32 s98, s80, s101
	s_addc_u32 s99, s81, 0
	s_add_u32 s98, s98, 0x34000000
	s_addc_u32 s99, s99, 0
	v_lshlrev_b32_e32 v234, 3, v158
	v_mov_b32_e32 v235, 0
	v_lshl_add_u64 v[234:235], s[98:99], 0, v[234:235]
	v_mov_b32_e32 v236, 0x800
	v_mov_b32_e32 v237, 0
	v_mov_b32_e32 v238, 0x400
	v_mov_b32_e32 v239, 0
	v_mov_b32_e32 v244, 0x100
	v_mov_b32_e32 v245, 0
	v_mov_b32_e32 v202, 0x1000
	v_mov_b32_e32 v203, 0
	v_mov_b32_e32 v195, 0
	global_load_dwordx4 v[224:227], v[232:233], off
	global_load_dwordx4 v[228:231], v[232:233], off offset:1024
	v_lshl_add_u64 v[232:233], v[232:233], 0, v[236:237]
	global_load_dwordx4 v[246:249], v[232:233], off
	global_load_dwordx4 v[250:253], v[232:233], off offset:1024
	v_lshl_add_u64 v[232:233], v[232:233], 0, v[236:237]

.Lmy_pc1:
	s_mov_b32 s32, s1
	s_cmp_lt_u32 s32, 20
	s_cbranch_scc1 .Lmy_tw1_w0
	s_cmp_gt_u32 s32, 126
	s_cbranch_scc1 .Lmy_tw1_w0
	s_waitcnt vmcnt(4)
	s_branch .Lmy_tw1_wd
